# attention K/V staging: all four 64-row K and V loads of a unit plus the k-gain loads (once, was 4x) issued up front and consumed with counted vmcnt waits (was 4 dependent load->norm->LDS-write rounds)
# speedup vs baseline: 1.0056x; 1.0056x over previous
; __device__ __forceinline__ float sum8(float s) { s += DPP_MOVF(s, 0xB1); s += DPP_MOVF(s, 0x4E); s += DPP_MOVF(s, 0x141); return s; }
; #define LAS __attribute__((address_space(3)))
; __device__ __forceinline__ unsigned pk2(float lo, float hi) { f32x2_t v = {lo, hi}; bf16x2_t b = __builtin_convertvector(v, bf16x2_t); return __builtin_bit_cast(unsigned, b); }
; __device__ __forceinline__ void attn_phase(int wave_s, LAS unsigned char* lds, const bf16* QKV, bf16* O, const float* qg, const float* kg, const float* sinks, const float* bt) {
;     ...
;         const long rowbase = (long)b * SEQ + (long)(nb - 1) * 128;
; #pragma unroll
;         for (int i = 0; i < 4; ++i) { int tq = tid; asm volatile("" : "+v"(tq)); const int p = tq + NTHR * i, jrow = p >> 3, ch = p & 7; const bool ok = (nb > 0) || (jrow >= 128);
;             v4u kw = (v4u){0u, 0u, 0u, 0u}, vw = (v4u){0u, 0u, 0u, 0u};
;             if (ok) { const bf16* src = QKV + (size_t)(rowbase + jrow) * NQKV + NH * HD + kvh * HD + ch * 8; kw = *(const v4u*)src; vw = *(const v4u*)(src + NKV * HD); }
;             float kf[8] = {bflo(kw.x), bfhi(kw.x), bflo(kw.y), bfhi(kw.y), bflo(kw.z), bfhi(kw.z), bflo(kw.w), bfhi(kw.w)};
;             float s = 0.f;
; #pragma unroll
;             for (int e = 0; e < 8; ++e) s += kf[e] * kf[e];
;             s = sum8(s);
;             const float rs = __builtin_amdgcn_rsqf(s * (1.0f / 64.0f) + EPS);
;             const f32x4 g0 = *(const f32x4*)(kg + ch * 8), g1 = *(const f32x4*)(kg + ch * 8 + 4);
;             v4u ko; ko.x = pk2(kf[0] * rs * g0.x, kf[1] * rs * g0.y); ko.y = pk2(kf[2] * rs * g0.z, kf[3] * rs * g0.w); ko.z = pk2(kf[4] * rs * g1.x, kf[5] * rs * g1.y); ko.w = pk2(kf[6] * rs * g1.z, kf[7] * rs * g1.w);
;             *(LAS v4u*)(Ks + jrow * KS_STRIDE + ch * 8) = ko;
;             LAS bf16* vd = Vt + (ch * 8) * VT_STRIDE + jrow;
;             vd[0 * VT_STRIDE] = (bf16)(vw.x & 0xffffu); vd[1 * VT_STRIDE] = (bf16)(vw.x >> 16); vd[2 * VT_STRIDE] = (bf16)(vw.y & 0xffffu); vd[3 * VT_STRIDE] = (bf16)(vw.y >> 16);
;             vd[4 * VT_STRIDE] = (bf16)(vw.z & 0xffffu); vd[5 * VT_STRIDE] = (bf16)(vw.z >> 16); vd[6 * VT_STRIDE] = (bf16)(vw.w & 0xffffu); vd[7 * VT_STRIDE] = (bf16)(vw.w >> 16); }
.LBB0_476:
	s_bfe_u32 s30, s35, 0x60002
	v_mov_b32_e32 v1, v142
	s_barrier
	v_add_co_u32_e64 v2, s[88:89], s30, -1
	s_xor_b64 s[10:11], s[88:89], -1
	v_ashrrev_i32_e32 v12, 3, v142
	v_and_b32_e32 v1, 7, v142
	s_ashr_i32 s6, s35, 8
	s_ashr_i32 s7, s6, 31
	v_ashrrev_i32_e32 v3, 31, v2
	s_and_b32 s31, s35, 3
	s_lshl_b64 s[8:9], s[6:7], 13
	v_lshlrev_b64 v[2:3], 7, v[2:3]
	v_lshl_add_u64 v[10:11], v[2:3], 0, s[8:9]
	s_lshl_b32 s12, s31, 6
	s_lshl_b32 s50, s12, 1
	s_and_b32 s36, s34, 3
	v_lshlrev_b32_e32 v14, 3, v1
	v_mov_b32_e32 v15, v0
	v_lshl_add_u64 v[20:21], v[14:15], 2, s[28:29]
	global_load_dwordx4 v[16:19], v[20:21], off
	s_nop 0
	global_load_dwordx4 v[20:23], v[20:21], off offset:16
	v_ashrrev_i32_e32 v13, 31, v12
	v_lshl_add_u64 v[2:3], v[10:11], 0, v[12:13]
	v_mov_b64_e32 v[4:5], s[26:27]
	v_mad_u64_u32 v[4:5], s[40:41], v2, s70, v[4:5]
	v_mad_i32_i24 v5, v3, s70, v5
	v_lshl_add_u64 v[2:3], v[4:5], 0, s[50:51]
	v_lshlrev_b32_e32 v4, 4, v1
	v_mov_b32_e32 v5, v0
	v_lshl_add_u64 v[2:3], v[2:3], 0, v[4:5]
	v_lshl_add_u64 v[76:77], v[2:3], 0, s[86:87]
	v_add_co_u32_e32 v68, vcc, 0x1000, v2
	s_lshl_b32 s2, s70, 6
	s_mov_b32 s3, 0
	v_addc_co_u32_e32 v69, vcc, 0, v3, vcc
	v_lshl_add_u64 v[70:71], v[68:69], 0, s[2:3]
	v_lshl_add_u64 v[78:79], v[76:77], 0, s[2:3]
	v_lshl_add_u64 v[72:73], v[70:71], 0, s[2:3]
	v_lshl_add_u64 v[80:81], v[78:79], 0, s[2:3]
	v_lshl_add_u64 v[74:75], v[72:73], 0, s[2:3]
	v_lshl_add_u64 v[82:83], v[80:81], 0, s[2:3]
	v_add_u32_e32 v24, 64, v12
	v_add_u32_e32 v25, 0x80, v12
	v_add_u32_e32 v26, 0xc0, v12
	v_mov_b64_e32 v[36:37], 0
	v_mov_b64_e32 v[38:39], 0
	v_mov_b64_e32 v[40:41], 0
	v_mov_b64_e32 v[42:43], 0
	v_mov_b64_e32 v[44:45], 0
	v_mov_b64_e32 v[46:47], 0
	v_mov_b64_e32 v[48:49], 0
	v_mov_b64_e32 v[50:51], 0
	v_mov_b64_e32 v[52:53], 0
	v_mov_b64_e32 v[54:55], 0
	v_mov_b64_e32 v[56:57], 0
	v_mov_b64_e32 v[58:59], 0
	v_mov_b64_e32 v[60:61], 0
	v_mov_b64_e32 v[62:63], 0
	v_mov_b64_e32 v[64:65], 0
	v_mov_b64_e32 v[66:67], 0
	v_mul_lo_u32 v32, v12, s67
	v_lshlrev_b32_e32 v33, 1, v14
	v_lshlrev_b32_e32 v34, 1, v12
	v_mul_u32_u24_e32 v35, 0x1040, v1
	v_add3_u32 v31, 0, v32, v33
	v_add3_u32 v35, 0, v35, v34
	s_mov_b64 s[84:85], exec
	v_cmp_gt_i32_e32 vcc, s66, v12
	s_and_b64 s[40:41], s[10:11], vcc
	s_andn2_b64 exec, s[84:85], s[40:41]
	global_load_dwordx4 v[36:39], v[68:69], off
	global_load_dwordx4 v[52:55], v[76:77], off offset:512
	s_mov_b64 exec, s[84:85]
	v_cmp_gt_i32_e32 vcc, s66, v24
	s_and_b64 s[40:41], s[10:11], vcc
	s_andn2_b64 exec, s[84:85], s[40:41]
	global_load_dwordx4 v[40:43], v[70:71], off
	global_load_dwordx4 v[56:59], v[78:79], off offset:512
	s_mov_b64 exec, s[84:85]
	v_cmp_gt_i32_e32 vcc, s66, v25
	s_and_b64 s[40:41], s[10:11], vcc
	s_andn2_b64 exec, s[84:85], s[40:41]
	global_load_dwordx4 v[44:47], v[72:73], off
	global_load_dwordx4 v[60:63], v[80:81], off offset:512
	s_mov_b64 exec, s[84:85]
	v_cmp_gt_i32_e32 vcc, s66, v26
	s_and_b64 s[40:41], s[10:11], vcc
	s_andn2_b64 exec, s[84:85], s[40:41]
	global_load_dwordx4 v[48:51], v[74:75], off
	global_load_dwordx4 v[64:67], v[82:83], off offset:512
	s_mov_b64 exec, s[84:85]
	s_lshl_b32 s2, s67, 6
	s_waitcnt vmcnt(7)
	v_lshlrev_b32_e32 v28, 16, v36
	v_and_b32_e32 v29, 0xffff0000, v36
	v_lshlrev_b32_e32 v24, 16, v39
	v_and_b32_e32 v25, 0xffff0000, v39
	v_lshlrev_b32_e32 v26, 16, v38
	v_and_b32_e32 v27, 0xffff0000, v38
	v_lshlrev_b32_e32 v8, 16, v37
	v_and_b32_e32 v9, 0xffff0000, v37
	v_pk_mul_f32 v[90:91], v[28:29], v[28:29]
	v_pk_mul_f32 v[84:85], v[8:9], v[8:9]
	v_add_f32_e32 v90, v90, v91
	v_add_f32_e32 v84, v84, v90
	v_pk_mul_f32 v[86:87], v[26:27], v[26:27]
	v_add_f32_e32 v84, v85, v84
	v_add_f32_e32 v86, v86, v84
	v_pk_mul_f32 v[6:7], v[24:25], v[24:25]
	v_add_f32_e32 v86, v87, v86
	v_add_f32_e32 v6, v6, v86
	v_add_f32_e32 v6, v7, v6
	s_nop 1
	v_add_f32_dpp v6, v6, v6 quad_perm:[1,0,3,2] row_mask:0xf bank_mask:0xf bound_ctrl:1
	s_nop 1
	v_add_f32_dpp v6, v6, v6 quad_perm:[2,3,0,1] row_mask:0xf bank_mask:0xf bound_ctrl:1
	s_nop 1
	v_add_f32_dpp v6, v6, v6 row_half_mirror row_mask:0xf bank_mask:0xf bound_ctrl:1
	v_fmamk_f32 v6, v6, 0x3c800000, v250
	v_rsq_f32_e32 v6, v6
	s_nop 0
	v_pk_mul_f32 v[84:85], v[6:7], v[28:29] op_sel_hi:[0,1]
	v_pk_mul_f32 v[8:9], v[6:7], v[8:9] op_sel_hi:[0,1]
	v_pk_mul_f32 v[86:87], v[6:7], v[26:27] op_sel_hi:[0,1]
	v_pk_mul_f32 v[6:7], v[6:7], v[24:25] op_sel_hi:[0,1]
	v_pk_mul_f32 v[84:85], v[16:17], v[84:85]
	v_pk_mul_f32 v[8:9], v[18:19], v[8:9]
	v_pk_mul_f32 v[86:87], v[20:21], v[86:87]
	v_pk_mul_f32 v[88:89], v[22:23], v[6:7]
	v_cvt_pk_bf16_f32 v6, v84, v85
	v_cvt_pk_bf16_f32 v7, v8, v9
	v_cvt_pk_bf16_f32 v8, v86, v87
	v_cvt_pk_bf16_f32 v9, v88, v89
	ds_write_b128 v31, v[6:9]
	v_add_u32_e32 v31, s2, v31
	s_waitcnt vmcnt(6)
	ds_write_b16 v35, v52 offset:36864
	ds_write_b16_d16_hi v35, v52 offset:37384
	ds_write_b16 v35, v53 offset:37904
	ds_write_b16_d16_hi v35, v53 offset:38424
	ds_write_b16 v35, v54 offset:38944
	ds_write_b16_d16_hi v35, v54 offset:39464
	ds_write_b16 v35, v55 offset:39984
	ds_write_b16_d16_hi v35, v55 offset:40504
	s_waitcnt vmcnt(5)
; __device__ __forceinline__ float sum8(float s) { s += DPP_MOVF(s, 0xB1); s += DPP_MOVF(s, 0x4E); s += DPP_MOVF(s, 0x141); return s; }
; #define LAS __attribute__((address_space(3)))
; __device__ __forceinline__ unsigned pk2(float lo, float hi) { f32x2_t v = {lo, hi}; bf16x2_t b = __builtin_convertvector(v, bf16x2_t); return __builtin_bit_cast(unsigned, b); }
; __device__ __forceinline__ void attn_phase(int wave_s, LAS unsigned char* lds, const bf16* QKV, bf16* O, const float* qg, const float* kg, const float* sinks, const float* bt) {
;     ...
;         for (int i = 0; i < 4; ++i) { int tq = tid; asm volatile("" : "+v"(tq)); const int p = tq + NTHR * i, jrow = p >> 3, ch = p & 7; const bool ok = (nb > 0) || (jrow >= 128);
;             v4u kw = (v4u){0u, 0u, 0u, 0u}, vw = (v4u){0u, 0u, 0u, 0u};
;             if (ok) { const bf16* src = QKV + (size_t)(rowbase + jrow) * NQKV + NH * HD + kvh * HD + ch * 8; kw = *(const v4u*)src; vw = *(const v4u*)(src + NKV * HD); }
;             float kf[8] = {bflo(kw.x), bfhi(kw.x), bflo(kw.y), bfhi(kw.y), bflo(kw.z), bfhi(kw.z), bflo(kw.w), bfhi(kw.w)};
;             float s = 0.f;
; #pragma unroll
;             for (int e = 0; e < 8; ++e) s += kf[e] * kf[e];
;             s = sum8(s);
;             const float rs = __builtin_amdgcn_rsqf(s * (1.0f / 64.0f) + EPS);
;             const f32x4 g0 = *(const f32x4*)(kg + ch * 8), g1 = *(const f32x4*)(kg + ch * 8 + 4);
;             v4u ko; ko.x = pk2(kf[0] * rs * g0.x, kf[1] * rs * g0.y); ko.y = pk2(kf[2] * rs * g0.z, kf[3] * rs * g0.w); ko.z = pk2(kf[4] * rs * g1.x, kf[5] * rs * g1.y); ko.w = pk2(kf[6] * rs * g1.z, kf[7] * rs * g1.w);
;             *(LAS v4u*)(Ks + jrow * KS_STRIDE + ch * 8) = ko;
;             LAS bf16* vd = Vt + (ch * 8) * VT_STRIDE + jrow;
;             vd[0 * VT_STRIDE] = (bf16)(vw.x & 0xffffu); vd[1 * VT_STRIDE] = (bf16)(vw.x >> 16); vd[2 * VT_STRIDE] = (bf16)(vw.y & 0xffffu); vd[3 * VT_STRIDE] = (bf16)(vw.y >> 16);
;             vd[4 * VT_STRIDE] = (bf16)(vw.z & 0xffffu); vd[5 * VT_STRIDE] = (bf16)(vw.z >> 16); vd[6 * VT_STRIDE] = (bf16)(vw.w & 0xffffu); vd[7 * VT_STRIDE] = (bf16)(vw.w >> 16); }
	v_lshlrev_b32_e32 v28, 16, v40
	v_and_b32_e32 v29, 0xffff0000, v40
	v_lshlrev_b32_e32 v24, 16, v43
	v_and_b32_e32 v25, 0xffff0000, v43
	v_lshlrev_b32_e32 v26, 16, v42
	v_and_b32_e32 v27, 0xffff0000, v42
	v_lshlrev_b32_e32 v8, 16, v41
	v_and_b32_e32 v9, 0xffff0000, v41
	v_pk_mul_f32 v[90:91], v[28:29], v[28:29]
	v_pk_mul_f32 v[84:85], v[8:9], v[8:9]
	v_add_f32_e32 v90, v90, v91
	v_add_f32_e32 v84, v84, v90
	v_pk_mul_f32 v[86:87], v[26:27], v[26:27]
	v_add_f32_e32 v84, v85, v84
	v_add_f32_e32 v86, v86, v84
	v_pk_mul_f32 v[6:7], v[24:25], v[24:25]
	v_add_f32_e32 v86, v87, v86
	v_add_f32_e32 v6, v6, v86
	v_add_f32_e32 v6, v7, v6
	s_nop 1
	v_add_f32_dpp v6, v6, v6 quad_perm:[1,0,3,2] row_mask:0xf bank_mask:0xf bound_ctrl:1
	s_nop 1
	v_add_f32_dpp v6, v6, v6 quad_perm:[2,3,0,1] row_mask:0xf bank_mask:0xf bound_ctrl:1
	s_nop 1
	v_add_f32_dpp v6, v6, v6 row_half_mirror row_mask:0xf bank_mask:0xf bound_ctrl:1
	v_fmamk_f32 v6, v6, 0x3c800000, v250
	v_rsq_f32_e32 v6, v6
	s_nop 0
	v_pk_mul_f32 v[84:85], v[6:7], v[28:29] op_sel_hi:[0,1]
	v_pk_mul_f32 v[8:9], v[6:7], v[8:9] op_sel_hi:[0,1]
	v_pk_mul_f32 v[86:87], v[6:7], v[26:27] op_sel_hi:[0,1]
	v_pk_mul_f32 v[6:7], v[6:7], v[24:25] op_sel_hi:[0,1]
	v_pk_mul_f32 v[84:85], v[16:17], v[84:85]
	v_pk_mul_f32 v[8:9], v[18:19], v[8:9]
	v_pk_mul_f32 v[86:87], v[20:21], v[86:87]
	v_pk_mul_f32 v[88:89], v[22:23], v[6:7]
	v_cvt_pk_bf16_f32 v6, v84, v85
	v_cvt_pk_bf16_f32 v7, v8, v9
	v_cvt_pk_bf16_f32 v8, v86, v87
	v_cvt_pk_bf16_f32 v9, v88, v89
	ds_write_b128 v31, v[6:9]
	v_add_u32_e32 v31, s2, v31
	s_waitcnt vmcnt(4)
	ds_write_b16 v35, v56 offset:36992
	ds_write_b16_d16_hi v35, v56 offset:37512
	ds_write_b16 v35, v57 offset:38032
	ds_write_b16_d16_hi v35, v57 offset:38552
	ds_write_b16 v35, v58 offset:39072
	ds_write_b16_d16_hi v35, v58 offset:39592
	ds_write_b16 v35, v59 offset:40112
	ds_write_b16_d16_hi v35, v59 offset:40632
	s_waitcnt vmcnt(3)
	v_lshlrev_b32_e32 v28, 16, v44
	v_and_b32_e32 v29, 0xffff0000, v44
	v_lshlrev_b32_e32 v24, 16, v47
	v_and_b32_e32 v25, 0xffff0000, v47
	v_lshlrev_b32_e32 v26, 16, v46
	v_and_b32_e32 v27, 0xffff0000, v46
	v_lshlrev_b32_e32 v8, 16, v45
	v_and_b32_e32 v9, 0xffff0000, v45
	v_pk_mul_f32 v[90:91], v[28:29], v[28:29]
	v_pk_mul_f32 v[84:85], v[8:9], v[8:9]
	v_add_f32_e32 v90, v90, v91
	v_add_f32_e32 v84, v84, v90
	v_pk_mul_f32 v[86:87], v[26:27], v[26:27]
	v_add_f32_e32 v84, v85, v84
	v_add_f32_e32 v86, v86, v84
	v_pk_mul_f32 v[6:7], v[24:25], v[24:25]
	v_add_f32_e32 v86, v87, v86
	v_add_f32_e32 v6, v6, v86
	v_add_f32_e32 v6, v7, v6
	s_nop 1
	v_add_f32_dpp v6, v6, v6 quad_perm:[1,0,3,2] row_mask:0xf bank_mask:0xf bound_ctrl:1
	s_nop 1
	v_add_f32_dpp v6, v6, v6 quad_perm:[2,3,0,1] row_mask:0xf bank_mask:0xf bound_ctrl:1
	s_nop 1
	v_add_f32_dpp v6, v6, v6 row_half_mirror row_mask:0xf bank_mask:0xf bound_ctrl:1
	v_fmamk_f32 v6, v6, 0x3c800000, v250
	v_rsq_f32_e32 v6, v6
	s_nop 0
	v_pk_mul_f32 v[84:85], v[6:7], v[28:29] op_sel_hi:[0,1]
	v_pk_mul_f32 v[8:9], v[6:7], v[8:9] op_sel_hi:[0,1]
	v_pk_mul_f32 v[86:87], v[6:7], v[26:27] op_sel_hi:[0,1]
	v_pk_mul_f32 v[6:7], v[6:7], v[24:25] op_sel_hi:[0,1]
	v_pk_mul_f32 v[84:85], v[16:17], v[84:85]
	v_pk_mul_f32 v[8:9], v[18:19], v[8:9]
	v_pk_mul_f32 v[86:87], v[20:21], v[86:87]
	v_pk_mul_f32 v[88:89], v[22:23], v[6:7]
	v_cvt_pk_bf16_f32 v6, v84, v85
	v_cvt_pk_bf16_f32 v7, v8, v9
	v_cvt_pk_bf16_f32 v8, v86, v87
	v_cvt_pk_bf16_f32 v9, v88, v89
	ds_write_b128 v31, v[6:9]
	v_add_u32_e32 v31, s2, v31
	s_waitcnt vmcnt(2)
	ds_write_b16 v35, v60 offset:37120
	ds_write_b16_d16_hi v35, v60 offset:37640
	ds_write_b16 v35, v61 offset:38160
	ds_write_b16_d16_hi v35, v61 offset:38680
	ds_write_b16 v35, v62 offset:39200
	ds_write_b16_d16_hi v35, v62 offset:39720
	ds_write_b16 v35, v63 offset:40240
	ds_write_b16_d16_hi v35, v63 offset:40760
	s_waitcnt vmcnt(1)
	v_lshlrev_b32_e32 v28, 16, v48
	v_and_b32_e32 v29, 0xffff0000, v48
	v_lshlrev_b32_e32 v24, 16, v51
	v_and_b32_e32 v25, 0xffff0000, v51
	v_lshlrev_b32_e32 v26, 16, v50
	v_and_b32_e32 v27, 0xffff0000, v50
	v_lshlrev_b32_e32 v8, 16, v49
	v_and_b32_e32 v9, 0xffff0000, v49
	v_pk_mul_f32 v[90:91], v[28:29], v[28:29]
	v_pk_mul_f32 v[84:85], v[8:9], v[8:9]
	v_add_f32_e32 v90, v90, v91
	v_add_f32_e32 v84, v84, v90
	v_pk_mul_f32 v[86:87], v[26:27], v[26:27]
	v_add_f32_e32 v84, v85, v84
	v_add_f32_e32 v86, v86, v84
	v_pk_mul_f32 v[6:7], v[24:25], v[24:25]
	v_add_f32_e32 v86, v87, v86
	v_add_f32_e32 v6, v6, v86
	v_add_f32_e32 v6, v7, v6
	s_nop 1
	v_add_f32_dpp v6, v6, v6 quad_perm:[1,0,3,2] row_mask:0xf bank_mask:0xf bound_ctrl:1
	s_nop 1
	v_add_f32_dpp v6, v6, v6 quad_perm:[2,3,0,1] row_mask:0xf bank_mask:0xf bound_ctrl:1
	s_nop 1
	v_add_f32_dpp v6, v6, v6 row_half_mirror row_mask:0xf bank_mask:0xf bound_ctrl:1
	v_fmamk_f32 v6, v6, 0x3c800000, v250
	v_rsq_f32_e32 v6, v6
	s_nop 0
	v_pk_mul_f32 v[84:85], v[6:7], v[28:29] op_sel_hi:[0,1]
	v_pk_mul_f32 v[8:9], v[6:7], v[8:9] op_sel_hi:[0,1]
	v_pk_mul_f32 v[86:87], v[6:7], v[26:27] op_sel_hi:[0,1]
	v_pk_mul_f32 v[6:7], v[6:7], v[24:25] op_sel_hi:[0,1]
	v_pk_mul_f32 v[84:85], v[16:17], v[84:85]
	v_pk_mul_f32 v[8:9], v[18:19], v[8:9]
	v_pk_mul_f32 v[86:87], v[20:21], v[86:87]
	v_pk_mul_f32 v[88:89], v[22:23], v[6:7]
	v_cvt_pk_bf16_f32 v6, v84, v85
	v_cvt_pk_bf16_f32 v7, v8, v9
	v_cvt_pk_bf16_f32 v8, v86, v87
	v_cvt_pk_bf16_f32 v9, v88, v89
	ds_write_b128 v31, v[6:9]
	s_waitcnt vmcnt(0)
	ds_write_b16 v35, v64 offset:37248
	ds_write_b16_d16_hi v35, v64 offset:37768
	ds_write_b16 v35, v65 offset:38288
	ds_write_b16_d16_hi v35, v65 offset:38808
	ds_write_b16 v35, v66 offset:39328
	ds_write_b16_d16_hi v35, v66 offset:39848
	ds_write_b16 v35, v67 offset:40368
	ds_write_b16_d16_hi v35, v67 offset:40888
	s_and_saveexec_b64 s[2:3], s[14:15]
	s_cbranch_execz .LBB0_497
; __device__ __forceinline__ void attn_phase(int wave_s, LAS unsigned char* lds, const bf16* QKV, bf16* O, const float* qg, const float* kg, const float* sinks, const float* bt) {
;     ...
;         for (int e = tid; e < 8 * 192; e += NTHR) { const int hh = e / 192, dist = e % 192 - 32; Bs[e] = (dist >= 0 && dist < 128) ? bt[(kvh * 8 + hh) * 128 + dist] - shift * LOG2E : -1e30f; }
	s_lshl_b32 s10, s36, 10
	s_sub_i32 s37, s10, 32
	s_mov_b32 s12, 0x2aaaaaab
	s_movk_i32 s13, 0xff40
	s_movk_i32 s40, 0xffe0
	s_add_i32 s10, 0, 0x11200
	v_lshl_add_u32 v1, v142, 2, s10
	v_add_u32_e32 v9, 0x200, v142
	v_add_u32_e32 v10, 0x400, v142
	v_mul_hi_i32 v11, v142, s12
	v_mul_hi_i32 v12, v9, s12
	v_mul_hi_i32 v13, v10, s12
	v_lshrrev_b32_e32 v14, 31, v11
	v_lshrrev_b32_e32 v15, 31, v12
	v_lshrrev_b32_e32 v16, 31, v13
	v_ashrrev_i32_e32 v11, 5, v11
	v_ashrrev_i32_e32 v12, 5, v12
	v_ashrrev_i32_e32 v13, 5, v13
	v_add_u32_e32 v11, v11, v14
	v_add_u32_e32 v12, v12, v15
	v_add_u32_e32 v13, v13, v16
	v_mul_lo_u32 v14, v11, s13
	v_mul_lo_u32 v15, v12, s13
	v_mul_lo_u32 v16, v13, s13
	v_add3_u32 v14, v142, v14, s40
	v_add3_u32 v15, v9, v15, s40
	v_add3_u32 v16, v10, v16, s40
	v_add_u32_e32 v18, s37, v142
	v_add_u32_e32 v20, s37, v9
	v_add_u32_e32 v22, s37, v10
	v_lshlrev_b32_e32 v11, 6, v11
	v_lshlrev_b32_e32 v12, 6, v12
	v_lshlrev_b32_e32 v13, 6, v13
	v_sub_u32_e32 v18, v18, v11
	v_sub_u32_e32 v20, v20, v12
	v_sub_u32_e32 v22, v22, v13
	v_ashrrev_i32_e32 v19, 31, v18
	v_ashrrev_i32_e32 v21, 31, v20
	v_ashrrev_i32_e32 v23, 31, v22
	v_lshl_add_u64 v[18:19], v[18:19], 2, s[20:21]
	v_lshl_add_u64 v[20:21], v[20:21], 2, s[20:21]
	v_lshl_add_u64 v[22:23], v[22:23], 2, s[20:21]
	v_cmp_gt_u32_e64 s[10:11], s66, v14
	v_cmp_gt_u32_e64 s[12:13], s66, v15
	v_cmp_gt_u32_e64 s[40:41], s66, v16
	v_mov_b32_e32 v27, 0xf149f2ca
	s_mov_b64 s[84:85], exec
	s_and_b64 exec, s[84:85], s[10:11]
	global_load_dword v24, v[18:19], off
	s_and_b64 exec, s[84:85], s[12:13]
	global_load_dword v25, v[20:21], off
	s_and_b64 exec, s[84:85], s[40:41]
	global_load_dword v26, v[22:23], off
	s_mov_b64 exec, s[84:85]
	s_waitcnt vmcnt(0)
	v_sub_f32_e32 v24, v24, v144
	v_sub_f32_e32 v25, v25, v144
	v_sub_f32_e32 v26, v26, v144
	v_cndmask_b32_e64 v24, v27, v24, s[10:11]
	v_cndmask_b32_e64 v25, v27, v25, s[12:13]
	v_cndmask_b32_e64 v26, v27, v26, s[40:41]
	ds_write_b32 v1, v24
	ds_write_b32 v1, v25 offset:2048
	ds_write_b32 v1, v26 offset:4096
